# LRU f32-MFMA re-tiled: one 16-row tile x 32 channels per wave (4 accumulator tiles share one A fragment), half the bank-conflicted LDS fragment reads
# baseline (speedup 1.0000x reference)
; __device__ __forceinline__ float softplusf_(float x) { return x > 20.f ? x : log1pf(expf(x)); }
; __device__ __forceinline__ const float* argf(int i) { return (const float*)kargs()[i]; }
; __device__ __forceinline__ rsrc_t mk_rsrc(const void* p) { return __builtin_amdgcn_make_buffer_rsrc((void*)p, 0, 0x7fffffff, 0x00020000); }
; __device__ __forceinline__ void lru_job(const bf16_t* P, bf16_t* Y, int l, int b, int kb, LAS float* lds, int wave_s) {
;     ...
;     const float ba = argf(16)[l * 256 + ch], bx = argf(18)[l * 256 + ch], spl = softplusf_(-argf(19)[l * 256 + ch]);
;     const float* cwp = argf(13) + l * 1024;
;     const float cw0 = cwp[ch], cw1 = cwp[256 + ch], cw2 = cwp[512 + ch], cw3 = cwp[768 + ch], cb = argf(14)[l * 256 + ch];
;     float hs = 0.f;
;     unsigned xn[8][4], gtn[8], gtc[8];
;     const rsrc_t rs = mk_rsrc(P);
;     const int rb2 = b * SEQ * INP * 2;
;     const rsrc_t ry = mk_rsrc(Y); const int yb2 = b * SEQ * D * 2, voY = (tg * D + 512 + ch) * 2;
;     const int voX = (tg * INP + ch) * 2;
;     ...
;     LRU_LOAD(0);
.LBB0_238:
	s_or_b64 exec, exec, s[4:5]
	s_mov_b64 s[4:5], s[0:1]
	s_load_dwordx2 s[4:5], s[4:5], 0x68
	s_mov_b64 s[6:7], s[0:1]
	v_add_u32_e32 v135, s67, v135
	v_ashrrev_i32_e32 v180, 6, v135
	v_mul_lo_u32 v162, v180, s78
	s_waitcnt lgkmcnt(0)
	v_lshl_add_u64 v[160:161], s[4:5], 0, v[36:37]
	flat_load_dword v156, v[160:161]
	flat_load_dword v157, v[160:161] offset:1024
	flat_load_dword v158, v[160:161] offset:2048
	flat_load_dword v159, v[160:161] offset:3072
	s_load_dwordx2 s[4:5], s[6:7], 0x70
	v_max_i32_e32 v163, 1, v180
	v_mul_lo_u32 v163, v163, s78
	v_or_b32_e32 v163, v163, v173
	v_lshl_add_u32 v163, v163, 1, v148
	s_waitcnt lgkmcnt(0)
	v_lshl_add_u64 v[160:161], s[4:5], 0, v[36:37]
	flat_load_dword v36, v[160:161]
	v_or_b32_e32 v160, v162, v173
	v_max_i32_e32 v161, 3, v180
	v_max_i32_e32 v162, 2, v180
	v_mul_lo_u32 v161, v161, s78
	v_mul_lo_u32 v162, v162, s78
	v_or_b32_e32 v161, v161, v173
	v_or_b32_e32 v162, v162, v173
	v_lshlrev_b32_e32 v160, 1, v160
	s_or_b32 s4, s65, 0x1008
	s_or_b32 s5, s65, 0x1208
	v_lshl_add_u32 v161, v161, 1, v146
	v_lshl_add_u32 v162, v162, 1, v147
	buffer_load_ushort v174, v161, s[16:19], s5 offen
	buffer_load_ushort v175, v162, s[16:19], s5 offen
	buffer_load_ushort v176, v163, s[16:19], s5 offen
	s_or_b32 s6, s65, 0xf008
	s_or_b32 s7, s65, 0x9e08
	s_or_b32 s8, s65, 0xba08
	s_or_b32 s9, s65, 0xd608
	s_or_b32 s10, s65, 0xf208
	s_or_b32 s11, s65, 0x1d008
	buffer_load_ushort v206, v160, s[16:19], s4 offen
	buffer_load_ushort v161, v160, s[16:19], s5 offen
	buffer_load_ushort v200, v160, s[16:19], s6 offen
	buffer_load_ushort v162, v160, s[16:19], s7 offen
	buffer_load_ushort v163, v160, s[16:19], s8 offen
	buffer_load_ushort v164, v160, s[16:19], s9 offen
	buffer_load_ushort v165, v160, s[16:19], s10 offen
	buffer_load_ushort v196, v160, s[16:19], s11 offen
	s_or_b32 s4, s65, 0x17e08
	s_or_b32 s5, s65, 0x19a08
	s_or_b32 s6, s65, 0x1b608
	s_or_b32 s7, s65, 0x1d208
	s_or_b32 s8, s65, 0x2b008
	s_or_b32 s9, s65, 0x25e08
	s_or_b32 s10, s65, 0x27a08
	s_or_b32 s11, s65, 0x29608
	buffer_load_ushort v166, v160, s[16:19], s4 offen
	buffer_load_ushort v167, v160, s[16:19], s5 offen
	buffer_load_ushort v168, v160, s[16:19], s6 offen
	buffer_load_ushort v169, v160, s[16:19], s7 offen
	buffer_load_ushort v194, v160, s[16:19], s8 offen
	buffer_load_ushort v170, v160, s[16:19], s9 offen
	buffer_load_ushort v171, v160, s[16:19], s10 offen
	buffer_load_ushort v172, v160, s[16:19], s11 offen
	s_or_b32 s4, s65, 0x2b208
	s_or_b32 s5, s65, 0x39008
	s_or_b32 s6, s65, 0x33e08
	s_or_b32 s7, s65, 0x35a08
	s_or_b32 s8, s65, 0x37608
	s_or_b32 s9, s65, 0x39208
	s_or_b32 s10, s65, 0x47008
	s_or_b32 s11, s65, 0x41e08
	buffer_load_ushort v179, v160, s[16:19], s4 offen
	buffer_load_ushort v193, v160, s[16:19], s5 offen
	buffer_load_ushort v183, v160, s[16:19], s6 offen
	buffer_load_ushort v185, v160, s[16:19], s7 offen
	buffer_load_ushort v189, v160, s[16:19], s8 offen
	buffer_load_ushort v190, v160, s[16:19], s9 offen
	buffer_load_ushort v188, v160, s[16:19], s10 offen
	buffer_load_ushort v192, v160, s[16:19], s11 offen
	s_or_b32 s4, s65, 0x43a08
	s_or_b32 s5, s65, 0x45608
	s_or_b32 s6, s65, 0x47208
	s_or_b32 s7, s65, 0x55008
	s_or_b32 s8, s65, 0x4fe08
	s_or_b32 s9, s65, 0x51a08
	s_or_b32 s10, s65, 0x53608
	s_or_b32 s11, s65, 0x55208
	buffer_load_ushort v197, v160, s[16:19], s4 offen
	buffer_load_ushort v198, v160, s[16:19], s5 offen
	buffer_load_ushort v199, v160, s[16:19], s6 offen
	buffer_load_ushort v187, v160, s[16:19], s7 offen
	buffer_load_ushort v202, v160, s[16:19], s8 offen
	buffer_load_ushort v204, v160, s[16:19], s9 offen
	buffer_load_ushort v205, v160, s[16:19], s10 offen
	buffer_load_ushort v207, v160, s[16:19], s11 offen
	s_or_b32 s4, s65, 0x63008
	buffer_load_ushort v184, v160, s[16:19], s4 offen
	s_or_b32 s4, s65, 0x5de08
	s_or_b32 s5, s65, 0x5fa08
	s_or_b32 s6, s65, 0x61608
	s_or_b32 s7, s65, 0x63208
	buffer_load_ushort v209, v160, s[16:19], s4 offen
	buffer_load_ushort v210, v160, s[16:19], s5 offen
	buffer_load_ushort v211, v160, s[16:19], s6 offen
	buffer_load_ushort v213, v160, s[16:19], s7 offen
	v_cmp_lt_i32_e32 vcc, 2, v180
	v_lshlrev_b32_e32 v177, 1, v173
	v_lshlrev_b32_e32 v182, 11, v180
	s_movk_i32 s4, 0x400
	v_and_b32_e32 v178, 0x3fffffc0, v135
	s_mov_b32 s9, 0
	s_or_b32 s8, s65, 0x70000
	s_waitcnt vmcnt(0)
; __device__ __forceinline__ float softplusf_(float x) { return x > 20.f ? x : log1pf(expf(x)); }
; __device__ __forceinline__ const float* argf(int i) { return (const float*)kargs()[i]; }
; __device__ __forceinline__ void lru_job(const bf16_t* P, bf16_t* Y, int l, int b, int kb, LAS float* lds, int wave_s) {
;     ...
;     f32x2_t wax[64];
;     { const float* wap = argf(15) + l * 16384; const float* wxp = argf(17) + l * 16384;
; #pragma unroll
;       for (int i = 0; i < 64; ++i) { wax[i].x = wap[(kb * 64 + i) * 64 + j]; wax[i].y = wxp[(kb * 64 + i) * 64 + j]; } }
;     const float ba = argf(16)[l * 256 + ch], bx = argf(18)[l * 256 + ch], spl = softplusf_(-argf(19)[l * 256 + ch]);
;     ...
;     LRU_LOAD(0);
	v_cndmask_b32_e32 v173, 0, v174, vcc
	v_cmp_lt_i32_e32 vcc, 1, v180
	v_mov_b32_e32 v186, v206
	v_mov_b32_e32 v191, v200
	v_cndmask_b32_e32 v174, 0, v175, vcc
	v_cmp_lt_i32_e32 vcc, 0, v180
	v_mov_b32_e32 v195, v196
	s_nop 0
	v_cndmask_b32_e32 v175, 0, v176, vcc
	v_or3_b32 v176, v182, v177, s4
	v_add_u32_e32 v177, 0, v134
	v_or_b32_e32 v134, v182, v134
	v_lshl_add_u32 v178, v178, 2, v177
	v_cmp_gt_i32_e32 vcc, 64, v135
	v_lshl_add_u32 v180, v180, 8, v177
	v_add_u32_e32 v181, 0, v134
	v_add_u32_e32 v182, 0, v182
	v_mov_b32_e32 v135, 0
	v_mov_b32_e32 v201, v194
	v_mov_b32_e32 v203, v193
	v_mov_b32_e32 v208, v188
	v_mov_b32_e32 v212, v187
	v_mov_b32_e32 v214, v184
	v_mbcnt_lo_u32_b32 v101, -1, 0
	v_mbcnt_hi_u32_b32 v101, -1, v101
	v_and_b32_e32 v102, 15, v101
	v_lshrrev_b32_e32 v103, 4, v101
	s_lshr_b32 s4, s67, 6
	s_and_b32 s5, s4, 3
	s_lshr_b32 s4, s4, 2
	s_lshl_b32 s6, s4, 5
	s_lshl_b32 s7, s5, 4
	v_add_u32_e32 v104, s6, v102
	v_lshlrev_b32_e32 v105, 2, v104
	v_add_u32_e32 v111, 64, v105
	ds_bpermute_b32 v96, v105, v132
	ds_bpermute_b32 v97, v105, v133
	ds_bpermute_b32 v98, v105, v39
	ds_bpermute_b32 v107, v111, v132
	ds_bpermute_b32 v108, v111, v133
	ds_bpermute_b32 v109, v111, v39
	v_add_u32_e32 v99, s7, v102
	v_lshlrev_b32_e32 v99, 8, v99
	v_lshl_add_u32 v99, v103, 6, v99
	v_lshl_add_u32 v100, v103, 2, s7
	v_lshlrev_b32_e32 v100, 8, v100
	v_add_u32_e32 v100, v100, v105
	v_add_u32_e32 v110, 64, v100
	v_lshlrev_b32_e32 v106, 12, v103
	v_lshl_add_u32 v106, v102, 2, v106
	s_load_dwordx2 s[10:11], s[0:1], 0x78
	s_lshl_b32 s4, s70, 14
	s_lshl_b32 s6, s6, 2
	s_add_u32 s4, s4, s6
	s_waitcnt lgkmcnt(0)
	s_add_u32 s10, s10, s4
	s_addc_u32 s11, s11, 0
	s_nop 4
	global_load_dword v0, v106, s[10:11] offset:0
	global_load_dword v1, v106, s[10:11] offset:256
	global_load_dword v2, v106, s[10:11] offset:512
	global_load_dword v3, v106, s[10:11] offset:768
	global_load_dword v4, v106, s[10:11] offset:1024
	global_load_dword v5, v106, s[10:11] offset:1280
	global_load_dword v6, v106, s[10:11] offset:1536
	global_load_dword v7, v106, s[10:11] offset:1792
	global_load_dword v8, v106, s[10:11] offset:2048
	global_load_dword v9, v106, s[10:11] offset:2304
	global_load_dword v10, v106, s[10:11] offset:2560
	global_load_dword v11, v106, s[10:11] offset:2816
	global_load_dword v12, v106, s[10:11] offset:3072
	global_load_dword v13, v106, s[10:11] offset:3328
	global_load_dword v14, v106, s[10:11] offset:3584
	global_load_dword v15, v106, s[10:11] offset:3840
	global_load_dword v56, v106, s[10:11] offset:64
	global_load_dword v57, v106, s[10:11] offset:320
	global_load_dword v58, v106, s[10:11] offset:576
	global_load_dword v59, v106, s[10:11] offset:832
	global_load_dword v60, v106, s[10:11] offset:1088
	global_load_dword v61, v106, s[10:11] offset:1344
	global_load_dword v62, v106, s[10:11] offset:1600
	global_load_dword v63, v106, s[10:11] offset:1856
	global_load_dword v64, v106, s[10:11] offset:2112
	global_load_dword v65, v106, s[10:11] offset:2368
	global_load_dword v66, v106, s[10:11] offset:2624
	global_load_dword v67, v106, s[10:11] offset:2880
	global_load_dword v68, v106, s[10:11] offset:3136
	global_load_dword v69, v106, s[10:11] offset:3392
	global_load_dword v70, v106, s[10:11] offset:3648
	global_load_dword v71, v106, s[10:11] offset:3904
	s_load_dwordx2 s[10:11], s[0:1], 0x88
	s_waitcnt lgkmcnt(0)
	s_add_u32 s10, s10, s4
	s_addc_u32 s11, s11, 0
	s_nop 4
	global_load_dword v16, v106, s[10:11] offset:0
	global_load_dword v17, v106, s[10:11] offset:256
	global_load_dword v18, v106, s[10:11] offset:512
	global_load_dword v19, v106, s[10:11] offset:768
	global_load_dword v20, v106, s[10:11] offset:1024
	global_load_dword v21, v106, s[10:11] offset:1280
	global_load_dword v22, v106, s[10:11] offset:1536
	global_load_dword v23, v106, s[10:11] offset:1792
	global_load_dword v24, v106, s[10:11] offset:2048
	global_load_dword v25, v106, s[10:11] offset:2304
	global_load_dword v26, v106, s[10:11] offset:2560
	global_load_dword v27, v106, s[10:11] offset:2816
	global_load_dword v28, v106, s[10:11] offset:3072
	global_load_dword v29, v106, s[10:11] offset:3328
	global_load_dword v30, v106, s[10:11] offset:3584
	global_load_dword v31, v106, s[10:11] offset:3840
	global_load_dword v112, v106, s[10:11] offset:64
	global_load_dword v113, v106, s[10:11] offset:320
	global_load_dword v114, v106, s[10:11] offset:576
	global_load_dword v115, v106, s[10:11] offset:832
	global_load_dword v116, v106, s[10:11] offset:1088
	global_load_dword v117, v106, s[10:11] offset:1344
	global_load_dword v118, v106, s[10:11] offset:1600
	global_load_dword v119, v106, s[10:11] offset:1856
	global_load_dword v120, v106, s[10:11] offset:2112
	global_load_dword v121, v106, s[10:11] offset:2368
	global_load_dword v122, v106, s[10:11] offset:2624
	global_load_dword v123, v106, s[10:11] offset:2880
	global_load_dword v124, v106, s[10:11] offset:3136
	global_load_dword v125, v106, s[10:11] offset:3392
	global_load_dword v126, v106, s[10:11] offset:3648
	global_load_dword v127, v106, s[10:11] offset:3904
	s_waitcnt vmcnt(0)
	s_branch .LBB0_240

; #define LAS __attribute__((address_space(3)))
; __device__ __forceinline__ void lru_job(const bf16_t* P, bf16_t* Y, int l, int b, int kb, LAS float* lds, int wave_s) {
;     ...
;         for (int tt = 0; tt < 8; ++tt) { const int t = tg * 8 + tt; f32x2_t dd = {ba, bx};
; #pragma unroll
;             for (int i4 = 0; i4 < 16; ++i4) { const f32x4 xv = *(const LAS f32x4*)(XC + t * 64 + 4 * i4);
; #pragma unroll
;                 for (int q = 0; q < 4; ++q) { const f32x2_t xb = {xv[q], xv[q]}; dd = __builtin_elementwise_fma(xb, wax[4 * i4 + q], dd); } }
.LBB0_242:
	ds_read_b128 v[40:43], v99
	ds_read_b128 v[44:47], v99 offset:16
	ds_read_b128 v[48:51], v99 offset:32
	ds_read_b128 v[52:55], v99 offset:48
	ds_read_b32 v88, v100
	ds_read_b32 v89, v100 offset:256
	ds_read_b32 v90, v100 offset:512
	ds_read_b32 v91, v100 offset:768
	ds_read_b32 v92, v110
	ds_read_b32 v93, v110 offset:256
	ds_read_b32 v94, v110 offset:512
	ds_read_b32 v95, v110 offset:768
	v_mov_b32_e32 v72, v96
	v_mov_b32_e32 v73, v96
	v_mov_b32_e32 v74, v96
	v_mov_b32_e32 v75, v96
	v_mov_b32_e32 v76, v97
	v_mov_b32_e32 v77, v97
	v_mov_b32_e32 v78, v97
	v_mov_b32_e32 v79, v97
	v_mov_b32_e32 v80, v107
	v_mov_b32_e32 v81, v107
	v_mov_b32_e32 v82, v107
	v_mov_b32_e32 v83, v107
	v_mov_b32_e32 v84, v108
	v_mov_b32_e32 v85, v108
	v_mov_b32_e32 v86, v108
	v_mov_b32_e32 v87, v108
	s_waitcnt lgkmcnt(11)
	s_nop 1
	v_mfma_f32_16x16x4_f32 v[72:75], v40, v0, v[72:75]
	v_mfma_f32_16x16x4_f32 v[76:79], v40, v16, v[76:79]
	v_mfma_f32_16x16x4_f32 v[80:83], v40, v56, v[80:83]
	v_mfma_f32_16x16x4_f32 v[84:87], v40, v112, v[84:87]
	v_mfma_f32_16x16x4_f32 v[72:75], v41, v1, v[72:75]
	v_mfma_f32_16x16x4_f32 v[76:79], v41, v17, v[76:79]
	v_mfma_f32_16x16x4_f32 v[80:83], v41, v57, v[80:83]
	v_mfma_f32_16x16x4_f32 v[84:87], v41, v113, v[84:87]
	v_mfma_f32_16x16x4_f32 v[72:75], v42, v2, v[72:75]
	v_mfma_f32_16x16x4_f32 v[76:79], v42, v18, v[76:79]
	v_mfma_f32_16x16x4_f32 v[80:83], v42, v58, v[80:83]
	v_mfma_f32_16x16x4_f32 v[84:87], v42, v114, v[84:87]
	v_mfma_f32_16x16x4_f32 v[72:75], v43, v3, v[72:75]
	v_mfma_f32_16x16x4_f32 v[76:79], v43, v19, v[76:79]
	v_mfma_f32_16x16x4_f32 v[80:83], v43, v59, v[80:83]
	v_mfma_f32_16x16x4_f32 v[84:87], v43, v115, v[84:87]
	s_waitcnt lgkmcnt(10)
	v_mfma_f32_16x16x4_f32 v[72:75], v44, v4, v[72:75]
	v_mfma_f32_16x16x4_f32 v[76:79], v44, v20, v[76:79]
	v_mfma_f32_16x16x4_f32 v[80:83], v44, v60, v[80:83]
	v_mfma_f32_16x16x4_f32 v[84:87], v44, v116, v[84:87]
	v_mfma_f32_16x16x4_f32 v[72:75], v45, v5, v[72:75]
	v_mfma_f32_16x16x4_f32 v[76:79], v45, v21, v[76:79]
	v_mfma_f32_16x16x4_f32 v[80:83], v45, v61, v[80:83]
	v_mfma_f32_16x16x4_f32 v[84:87], v45, v117, v[84:87]
	v_mfma_f32_16x16x4_f32 v[72:75], v46, v6, v[72:75]
	v_mfma_f32_16x16x4_f32 v[76:79], v46, v22, v[76:79]
	v_mfma_f32_16x16x4_f32 v[80:83], v46, v62, v[80:83]
	v_mfma_f32_16x16x4_f32 v[84:87], v46, v118, v[84:87]
	v_mfma_f32_16x16x4_f32 v[72:75], v47, v7, v[72:75]
	v_mfma_f32_16x16x4_f32 v[76:79], v47, v23, v[76:79]
	v_mfma_f32_16x16x4_f32 v[80:83], v47, v63, v[80:83]
	v_mfma_f32_16x16x4_f32 v[84:87], v47, v119, v[84:87]
	s_waitcnt lgkmcnt(9)
	v_mfma_f32_16x16x4_f32 v[72:75], v48, v8, v[72:75]
	v_mfma_f32_16x16x4_f32 v[76:79], v48, v24, v[76:79]
	v_mfma_f32_16x16x4_f32 v[80:83], v48, v64, v[80:83]
	v_mfma_f32_16x16x4_f32 v[84:87], v48, v120, v[84:87]
	v_mfma_f32_16x16x4_f32 v[72:75], v49, v9, v[72:75]
	v_mfma_f32_16x16x4_f32 v[76:79], v49, v25, v[76:79]
	v_mfma_f32_16x16x4_f32 v[80:83], v49, v65, v[80:83]
	v_mfma_f32_16x16x4_f32 v[84:87], v49, v121, v[84:87]
	v_mfma_f32_16x16x4_f32 v[72:75], v50, v10, v[72:75]
	v_mfma_f32_16x16x4_f32 v[76:79], v50, v26, v[76:79]
	v_mfma_f32_16x16x4_f32 v[80:83], v50, v66, v[80:83]
	v_mfma_f32_16x16x4_f32 v[84:87], v50, v122, v[84:87]
	v_mfma_f32_16x16x4_f32 v[72:75], v51, v11, v[72:75]
	v_mfma_f32_16x16x4_f32 v[76:79], v51, v27, v[76:79]
	v_mfma_f32_16x16x4_f32 v[80:83], v51, v67, v[80:83]
	v_mfma_f32_16x16x4_f32 v[84:87], v51, v123, v[84:87]
	s_waitcnt lgkmcnt(8)
	v_mfma_f32_16x16x4_f32 v[72:75], v52, v12, v[72:75]
	v_mfma_f32_16x16x4_f32 v[76:79], v52, v28, v[76:79]
	v_mfma_f32_16x16x4_f32 v[80:83], v52, v68, v[80:83]
	v_mfma_f32_16x16x4_f32 v[84:87], v52, v124, v[84:87]
	v_mfma_f32_16x16x4_f32 v[72:75], v53, v13, v[72:75]
	v_mfma_f32_16x16x4_f32 v[76:79], v53, v29, v[76:79]
	v_mfma_f32_16x16x4_f32 v[80:83], v53, v69, v[80:83]
	v_mfma_f32_16x16x4_f32 v[84:87], v53, v125, v[84:87]
	v_mfma_f32_16x16x4_f32 v[72:75], v54, v14, v[72:75]
	v_mfma_f32_16x16x4_f32 v[76:79], v54, v30, v[76:79]
	v_mfma_f32_16x16x4_f32 v[80:83], v54, v70, v[80:83]
	v_mfma_f32_16x16x4_f32 v[84:87], v54, v126, v[84:87]
	v_mfma_f32_16x16x4_f32 v[72:75], v55, v15, v[72:75]
	v_mfma_f32_16x16x4_f32 v[76:79], v55, v31, v[76:79]
	v_mfma_f32_16x16x4_f32 v[80:83], v55, v71, v[80:83]
	v_mfma_f32_16x16x4_f32 v[84:87], v55, v127, v[84:87]
	s_waitcnt lgkmcnt(0)
; __device__ __forceinline__ float sigmoidf_(float x) { return __builtin_amdgcn_rcpf(1.f + __expf(-x)); }
; __device__ __forceinline__ void lru_job(const bf16_t* P, bf16_t* Y, int l, int b, int kb, LAS float* lds, int wave_s) {
;     ...
;             const float rg = sigmoidf_(dd.x), ig = sigmoidf_(dd.y);
;             const float la = -8.f * rg * spl;
;             const float av = __expf(la);
;             Aa[t * 64 + j] = av;
;             Uu[t * 64 + j] = sqrtf(fmaxf(1.f - av * av, 0.f)) * (ig * XC[t * 64 + j]); }
	s_nop 7
	s_nop 3
	v_mul_f32_e32 v101, 0xbfb8aa3b, v72
	v_mul_f32_e32 v104, 0xbfb8aa3b, v73
	v_exp_f32_e32 v101, v101
	v_exp_f32_e32 v104, v104
	v_mul_f32_e32 v102, 0xbfb8aa3b, v76
	v_mul_f32_e32 v105, 0xbfb8aa3b, v77
	v_exp_f32_e32 v102, v102
	v_exp_f32_e32 v105, v105
	v_add_f32_e32 v101, 1.0, v101
	v_add_f32_e32 v104, 1.0, v104
	v_rcp_f32_e32 v101, v101
	v_rcp_f32_e32 v104, v104
	v_add_f32_e32 v102, 1.0, v102
	v_add_f32_e32 v105, 1.0, v105
	v_rcp_f32_e32 v102, v102
	v_rcp_f32_e32 v105, v105
	v_mul_f32_e32 v101, 0xc1000000, v101
	v_mul_f32_e32 v104, 0xc1000000, v104
	v_mul_f32_e32 v101, v98, v101
	v_mul_f32_e32 v104, v98, v104
	v_mul_f32_e32 v101, 0x3fb8aa3b, v101
	v_mul_f32_e32 v104, 0x3fb8aa3b, v104
	v_exp_f32_e32 v101, v101
	v_exp_f32_e32 v104, v104
	v_mul_f32_e32 v102, v88, v102
	v_mul_f32_e32 v105, v89, v105
	v_fma_f32 v103, -v101, v101, 1.0
	v_fma_f32 v106, -v104, v104, 1.0
	v_max_f32_e32 v103, 0, v103
	v_max_f32_e32 v106, 0, v106
	v_sqrt_f32_e32 v103, v103
	v_sqrt_f32_e32 v106, v106
	s_nop 0
	s_nop 0
	v_mul_f32_e32 v102, v102, v103
	v_mul_f32_e32 v105, v105, v106
	ds_write2st64_b32 v100, v101, v102 offset0:64 offset1:128
	ds_write2st64_b32 v100, v104, v105 offset0:65 offset1:129
	v_mul_f32_e32 v101, 0xbfb8aa3b, v74
	v_mul_f32_e32 v104, 0xbfb8aa3b, v75
	v_exp_f32_e32 v101, v101
	v_exp_f32_e32 v104, v104
	v_mul_f32_e32 v102, 0xbfb8aa3b, v78
	v_mul_f32_e32 v105, 0xbfb8aa3b, v79
	v_exp_f32_e32 v102, v102
	v_exp_f32_e32 v105, v105
	v_add_f32_e32 v101, 1.0, v101
	v_add_f32_e32 v104, 1.0, v104
	v_rcp_f32_e32 v101, v101
	v_rcp_f32_e32 v104, v104
	v_add_f32_e32 v102, 1.0, v102
	v_add_f32_e32 v105, 1.0, v105
	v_rcp_f32_e32 v102, v102
	v_rcp_f32_e32 v105, v105
	v_mul_f32_e32 v101, 0xc1000000, v101
	v_mul_f32_e32 v104, 0xc1000000, v104
	v_mul_f32_e32 v101, v98, v101
	v_mul_f32_e32 v104, v98, v104
	v_mul_f32_e32 v101, 0x3fb8aa3b, v101
	v_mul_f32_e32 v104, 0x3fb8aa3b, v104
	v_exp_f32_e32 v101, v101
	v_exp_f32_e32 v104, v104
	v_mul_f32_e32 v102, v90, v102
	v_mul_f32_e32 v105, v91, v105
	v_fma_f32 v103, -v101, v101, 1.0
	v_fma_f32 v106, -v104, v104, 1.0
	v_max_f32_e32 v103, 0, v103
	v_max_f32_e32 v106, 0, v106
	v_sqrt_f32_e32 v103, v103
	v_sqrt_f32_e32 v106, v106
	s_nop 0
	s_nop 0
	v_mul_f32_e32 v102, v102, v103
	v_mul_f32_e32 v105, v105, v106
	ds_write2st64_b32 v100, v101, v102 offset0:66 offset1:130
	ds_write2st64_b32 v100, v104, v105 offset0:67 offset1:131
	v_mul_f32_e32 v101, 0xbfb8aa3b, v80
	v_mul_f32_e32 v104, 0xbfb8aa3b, v81
	v_exp_f32_e32 v101, v101
	v_exp_f32_e32 v104, v104
	v_mul_f32_e32 v102, 0xbfb8aa3b, v84
	v_mul_f32_e32 v105, 0xbfb8aa3b, v85
	v_exp_f32_e32 v102, v102
	v_exp_f32_e32 v105, v105
	v_add_f32_e32 v101, 1.0, v101
	v_add_f32_e32 v104, 1.0, v104
	v_rcp_f32_e32 v101, v101
	v_rcp_f32_e32 v104, v104
	v_add_f32_e32 v102, 1.0, v102
	v_add_f32_e32 v105, 1.0, v105
	v_rcp_f32_e32 v102, v102
	v_rcp_f32_e32 v105, v105
	v_mul_f32_e32 v101, 0xc1000000, v101
	v_mul_f32_e32 v104, 0xc1000000, v104
	v_mul_f32_e32 v101, v109, v101
	v_mul_f32_e32 v104, v109, v104
	v_mul_f32_e32 v101, 0x3fb8aa3b, v101
	v_mul_f32_e32 v104, 0x3fb8aa3b, v104
	v_exp_f32_e32 v101, v101
	v_exp_f32_e32 v104, v104
	v_mul_f32_e32 v102, v92, v102
	v_mul_f32_e32 v105, v93, v105
	v_fma_f32 v103, -v101, v101, 1.0
	v_fma_f32 v106, -v104, v104, 1.0
	v_max_f32_e32 v103, 0, v103
	v_max_f32_e32 v106, 0, v106
	v_sqrt_f32_e32 v103, v103
	v_sqrt_f32_e32 v106, v106
	s_nop 0
	s_nop 0
	v_mul_f32_e32 v102, v102, v103
	v_mul_f32_e32 v105, v105, v106
	ds_write2st64_b32 v110, v101, v102 offset0:64 offset1:128
	ds_write2st64_b32 v110, v104, v105 offset0:65 offset1:129
	v_mul_f32_e32 v101, 0xbfb8aa3b, v82
	v_mul_f32_e32 v104, 0xbfb8aa3b, v83
	v_exp_f32_e32 v101, v101
	v_exp_f32_e32 v104, v104
	v_mul_f32_e32 v102, 0xbfb8aa3b, v86
	v_mul_f32_e32 v105, 0xbfb8aa3b, v87
	v_exp_f32_e32 v102, v102
	v_exp_f32_e32 v105, v105
	v_add_f32_e32 v101, 1.0, v101
	v_add_f32_e32 v104, 1.0, v104
	v_rcp_f32_e32 v101, v101
	v_rcp_f32_e32 v104, v104
	v_add_f32_e32 v102, 1.0, v102
	v_add_f32_e32 v105, 1.0, v105
	v_rcp_f32_e32 v102, v102
	v_rcp_f32_e32 v105, v105
	v_mul_f32_e32 v101, 0xc1000000, v101
	v_mul_f32_e32 v104, 0xc1000000, v104
	v_mul_f32_e32 v101, v109, v101
	v_mul_f32_e32 v104, v109, v104
	v_mul_f32_e32 v101, 0x3fb8aa3b, v101
	v_mul_f32_e32 v104, 0x3fb8aa3b, v104
	v_exp_f32_e32 v101, v101
	v_exp_f32_e32 v104, v104
	v_mul_f32_e32 v102, v94, v102
	v_mul_f32_e32 v105, v95, v105
	v_fma_f32 v103, -v101, v101, 1.0
	v_fma_f32 v106, -v104, v104, 1.0
	v_max_f32_e32 v103, 0, v103
	v_max_f32_e32 v106, 0, v106
	v_sqrt_f32_e32 v103, v103
	v_sqrt_f32_e32 v106, v106
	s_nop 0
	s_nop 0
	v_mul_f32_e32 v102, v102, v103
	v_mul_f32_e32 v105, v105, v106
	ds_write2st64_b32 v110, v101, v102 offset0:66 offset1:130
	ds_write2st64_b32 v110, v104, v105 offset0:67 offset1:131
	s_waitcnt lgkmcnt(0)
	s_barrier
	s_and_saveexec_b64 s[4:5], vcc
	s_cbranch_execz .LBB0_239
; __device__ __forceinline__ void lru_job(const bf16_t* P, bf16_t* Y, int l, int b, int kb, LAS float* lds, int wave_s) {
;     ...
;         if (tid < 64) {
;             for (int tb = 0; tb < TC; tb += 8) { float av[8], uv[8];
; #pragma unroll
;                 for (int k = 0; k < 8; ++k) { av[k] = Aa[(tb + k) * 64 + j]; uv[k] = Uu[(tb + k) * 64 + j]; }
; #pragma unroll
;                 for (int k = 0; k < 8; ++k) { hs = av[k] * hs + uv[k]; Hh[(tb + k) * 64 + j] = hs; } }
;         }
	ds_read2st64_b32 v[216:217], v177 offset0:64 offset1:65
	ds_read2st64_b32 v[218:219], v177 offset0:66 offset1:67
	ds_read2st64_b32 v[220:221], v177 offset0:68 offset1:69
	ds_read2st64_b32 v[222:223], v177 offset0:70 offset1:71
	ds_read2st64_b32 v[224:225], v177 offset0:128 offset1:129
	ds_read2st64_b32 v[226:227], v177 offset0:130 offset1:131
	ds_read2st64_b32 v[228:229], v177 offset0:132 offset1:133
	ds_read2st64_b32 v[230:231], v177 offset0:134 offset1:135
	ds_read2st64_b32 v[234:235], v177 offset0:72 offset1:73
	ds_read2st64_b32 v[236:237], v177 offset0:74 offset1:75
	ds_read2st64_b32 v[238:239], v177 offset0:76 offset1:77
	ds_read2st64_b32 v[240:241], v177 offset0:78 offset1:79
	ds_read2st64_b32 v[242:243], v177 offset0:136 offset1:137
	ds_read2st64_b32 v[244:245], v177 offset0:138 offset1:139
	ds_read2st64_b32 v[246:247], v177 offset0:140 offset1:141
	ds_read2st64_b32 v[248:249], v177 offset0:142 offset1:143
	s_waitcnt lgkmcnt(8)
	v_fmac_f32_e32 v224, v135, v216
	v_fmac_f32_e32 v225, v224, v217
	v_fmac_f32_e32 v226, v225, v218
	v_fmac_f32_e32 v227, v226, v219
	v_fmac_f32_e32 v228, v227, v220
	v_fmac_f32_e32 v229, v228, v221
	v_fmac_f32_e32 v230, v229, v222
	v_fmac_f32_e32 v231, v230, v223
	ds_write2st64_b32 v177, v224, v225 offset0:192 offset1:193
	ds_write2st64_b32 v177, v226, v227 offset0:194 offset1:195
	ds_write2st64_b32 v177, v228, v229 offset0:196 offset1:197
	ds_write2st64_b32 v177, v230, v231 offset0:198 offset1:199
	ds_read2st64_b32 v[216:217], v177 offset0:80 offset1:81
	ds_read2st64_b32 v[218:219], v177 offset0:82 offset1:83
	ds_read2st64_b32 v[220:221], v177 offset0:84 offset1:85
	ds_read2st64_b32 v[222:223], v177 offset0:86 offset1:87
	ds_read2st64_b32 v[224:225], v177 offset0:144 offset1:145
	ds_read2st64_b32 v[226:227], v177 offset0:146 offset1:147
	ds_read2st64_b32 v[228:229], v177 offset0:148 offset1:149
	ds_read2st64_b32 v[230:231], v177 offset0:150 offset1:151
	s_waitcnt lgkmcnt(12)
	v_fmac_f32_e32 v242, v231, v234
	v_fmac_f32_e32 v243, v242, v235
	v_fmac_f32_e32 v244, v243, v236
	v_fmac_f32_e32 v245, v244, v237
	v_fmac_f32_e32 v246, v245, v238
	v_fmac_f32_e32 v247, v246, v239
	v_fmac_f32_e32 v248, v247, v240
	v_fmac_f32_e32 v249, v248, v241
	ds_write2st64_b32 v177, v242, v243 offset0:200 offset1:201
	ds_write2st64_b32 v177, v244, v245 offset0:202 offset1:203
	ds_write2st64_b32 v177, v246, v247 offset0:204 offset1:205
	ds_write2st64_b32 v177, v248, v249 offset0:206 offset1:207
	ds_read2st64_b32 v[234:235], v177 offset0:88 offset1:89
	ds_read2st64_b32 v[236:237], v177 offset0:90 offset1:91
	ds_read2st64_b32 v[238:239], v177 offset0:92 offset1:93
	ds_read2st64_b32 v[240:241], v177 offset0:94 offset1:95
	ds_read2st64_b32 v[242:243], v177 offset0:152 offset1:153
	ds_read2st64_b32 v[244:245], v177 offset0:154 offset1:155
	ds_read2st64_b32 v[246:247], v177 offset0:156 offset1:157
	ds_read2st64_b32 v[248:249], v177 offset0:158 offset1:159
	s_waitcnt lgkmcnt(12)
	v_fmac_f32_e32 v224, v249, v216
	v_fmac_f32_e32 v225, v224, v217
	v_fmac_f32_e32 v226, v225, v218
	v_fmac_f32_e32 v227, v226, v219
	v_fmac_f32_e32 v228, v227, v220
	v_fmac_f32_e32 v229, v228, v221
	v_fmac_f32_e32 v230, v229, v222
	v_fmac_f32_e32 v231, v230, v223
	ds_write2st64_b32 v177, v224, v225 offset0:208 offset1:209
	ds_write2st64_b32 v177, v226, v227 offset0:210 offset1:211
	ds_write2st64_b32 v177, v228, v229 offset0:212 offset1:213
	ds_write2st64_b32 v177, v230, v231 offset0:214 offset1:215
	ds_read2st64_b32 v[216:217], v177 offset0:96 offset1:97
	ds_read2st64_b32 v[218:219], v177 offset0:98 offset1:99
	ds_read2st64_b32 v[220:221], v177 offset0:100 offset1:101
	ds_read2st64_b32 v[222:223], v177 offset0:102 offset1:103
	ds_read2st64_b32 v[224:225], v177 offset0:160 offset1:161
	ds_read2st64_b32 v[226:227], v177 offset0:162 offset1:163
	ds_read2st64_b32 v[228:229], v177 offset0:164 offset1:165
	ds_read2st64_b32 v[230:231], v177 offset0:166 offset1:167
	s_waitcnt lgkmcnt(12)
; __device__ __forceinline__ void lru_job(const bf16_t* P, bf16_t* Y, int l, int b, int kb, LAS float* lds, int wave_s) {
;     ...
;         if (tid < 64) {
;             for (int tb = 0; tb < TC; tb += 8) { float av[8], uv[8];
; #pragma unroll
;                 for (int k = 0; k < 8; ++k) { av[k] = Aa[(tb + k) * 64 + j]; uv[k] = Uu[(tb + k) * 64 + j]; }
; #pragma unroll
;                 for (int k = 0; k < 8; ++k) { hs = av[k] * hs + uv[k]; Hh[(tb + k) * 64 + j] = hs; } }
;         }
	v_fmac_f32_e32 v242, v231, v234
	v_fmac_f32_e32 v243, v242, v235
	v_fmac_f32_e32 v244, v243, v236
	v_fmac_f32_e32 v245, v244, v237
	v_fmac_f32_e32 v246, v245, v238
	v_fmac_f32_e32 v247, v246, v239
	v_fmac_f32_e32 v248, v247, v240
	v_fmac_f32_e32 v249, v248, v241
	ds_write2st64_b32 v177, v242, v243 offset0:216 offset1:217
	ds_write2st64_b32 v177, v244, v245 offset0:218 offset1:219
	ds_write2st64_b32 v177, v246, v247 offset0:220 offset1:221
	ds_write2st64_b32 v177, v248, v249 offset0:222 offset1:223
	ds_read2st64_b32 v[234:235], v177 offset0:104 offset1:105
	ds_read2st64_b32 v[236:237], v177 offset0:106 offset1:107
	ds_read2st64_b32 v[238:239], v177 offset0:108 offset1:109
	ds_read2st64_b32 v[240:241], v177 offset0:110 offset1:111
	ds_read2st64_b32 v[242:243], v177 offset0:168 offset1:169
	ds_read2st64_b32 v[244:245], v177 offset0:170 offset1:171
	ds_read2st64_b32 v[246:247], v177 offset0:172 offset1:173
	ds_read2st64_b32 v[248:249], v177 offset0:174 offset1:175
	s_waitcnt lgkmcnt(12)
	v_fmac_f32_e32 v224, v249, v216
	v_fmac_f32_e32 v225, v224, v217
	v_fmac_f32_e32 v226, v225, v218
	v_fmac_f32_e32 v227, v226, v219
	v_fmac_f32_e32 v228, v227, v220
	v_fmac_f32_e32 v229, v228, v221
	v_fmac_f32_e32 v230, v229, v222
	v_fmac_f32_e32 v231, v230, v223
	ds_write2st64_b32 v177, v224, v225 offset0:224 offset1:225
	ds_write2st64_b32 v177, v226, v227 offset0:226 offset1:227
	ds_write2st64_b32 v177, v228, v229 offset0:228 offset1:229
	ds_write2st64_b32 v177, v230, v231 offset0:230 offset1:231
	ds_read2st64_b32 v[216:217], v177 offset0:112 offset1:113
	ds_read2st64_b32 v[218:219], v177 offset0:114 offset1:115
	ds_read2st64_b32 v[220:221], v177 offset0:116 offset1:117
	ds_read2st64_b32 v[222:223], v177 offset0:118 offset1:119
	ds_read2st64_b32 v[224:225], v177 offset0:176 offset1:177
	ds_read2st64_b32 v[226:227], v177 offset0:178 offset1:179
	ds_read2st64_b32 v[228:229], v177 offset0:180 offset1:181
	ds_read2st64_b32 v[230:231], v177 offset0:182 offset1:183
	s_waitcnt lgkmcnt(12)
	v_fmac_f32_e32 v242, v231, v234
	v_fmac_f32_e32 v243, v242, v235
	v_fmac_f32_e32 v244, v243, v236
	v_fmac_f32_e32 v245, v244, v237
	v_fmac_f32_e32 v246, v245, v238
	v_fmac_f32_e32 v247, v246, v239
	v_fmac_f32_e32 v248, v247, v240
	v_fmac_f32_e32 v249, v248, v241
	ds_write2st64_b32 v177, v242, v243 offset0:232 offset1:233
	ds_write2st64_b32 v177, v244, v245 offset0:234 offset1:235
	ds_write2st64_b32 v177, v246, v247 offset0:236 offset1:237
	ds_write2st64_b32 v177, v248, v249 offset0:238 offset1:239
	ds_read2st64_b32 v[234:235], v177 offset0:120 offset1:121
	ds_read2st64_b32 v[236:237], v177 offset0:122 offset1:123
	ds_read2st64_b32 v[238:239], v177 offset0:124 offset1:125
	ds_read2st64_b32 v[240:241], v177 offset0:126 offset1:127
	ds_read2st64_b32 v[242:243], v177 offset0:184 offset1:185
	ds_read2st64_b32 v[244:245], v177 offset0:186 offset1:187
	ds_read2st64_b32 v[246:247], v177 offset0:188 offset1:189
	ds_read2st64_b32 v[248:249], v177 offset0:190 offset1:191
	s_waitcnt lgkmcnt(12)
	v_fmac_f32_e32 v224, v249, v216
	v_fmac_f32_e32 v225, v224, v217
	v_fmac_f32_e32 v226, v225, v218
	v_fmac_f32_e32 v227, v226, v219
	v_fmac_f32_e32 v228, v227, v220
	v_fmac_f32_e32 v229, v228, v221
	v_fmac_f32_e32 v230, v229, v222
	v_fmac_f32_e32 v231, v230, v223
	ds_write2st64_b32 v177, v224, v225 offset0:240 offset1:241
	ds_write2st64_b32 v177, v226, v227 offset0:242 offset1:243
	ds_write2st64_b32 v177, v228, v229 offset0:244 offset1:245
	ds_write2st64_b32 v177, v230, v231 offset0:246 offset1:247
	s_waitcnt lgkmcnt(4)
	v_fmac_f32_e32 v242, v231, v234
	v_fmac_f32_e32 v243, v242, v235
	v_fmac_f32_e32 v244, v243, v236
	v_fmac_f32_e32 v245, v244, v237
	v_fmac_f32_e32 v246, v245, v238
	v_fmac_f32_e32 v247, v246, v239
	v_fmac_f32_e32 v248, v247, v240
	v_fmac_f32_e32 v249, v248, v241
	ds_write2st64_b32 v177, v242, v243 offset0:248 offset1:249
	ds_write2st64_b32 v177, v244, v245 offset0:250 offset1:251
	ds_write2st64_b32 v177, v246, v247 offset0:252 offset1:253
	ds_write2st64_b32 v177, v248, v249 offset0:254 offset1:255
	v_mov_b32_e32 v135, v249
	s_branch .LBB0_239

; __device__ __forceinline__ float softplusf_(float x) { return x > 20.f ? x : log1pf(expf(x)); }
; __device__ __forceinline__ const float* argf(int i) { return (const float*)kargs()[i]; }
; __device__ __forceinline__ rsrc_t mk_rsrc(const void* p) { return __builtin_amdgcn_make_buffer_rsrc((void*)p, 0, 0x7fffffff, 0x00020000); }
; __device__ __forceinline__ void lru_job(const bf16_t* P, bf16_t* Y, int l, int b, int kb, LAS float* lds, int wave_s) {
;     ...
;     const float ba = argf(16)[l * 256 + ch], bx = argf(18)[l * 256 + ch], spl = softplusf_(-argf(19)[l * 256 + ch]);
;     const float* cwp = argf(13) + l * 1024;
;     const float cw0 = cwp[ch], cw1 = cwp[256 + ch], cw2 = cwp[512 + ch], cw3 = cwp[768 + ch], cb = argf(14)[l * 256 + ch];
;     float hs = 0.f;
;     unsigned xn[8][4], gtn[8], gtc[8];
;     const rsrc_t rs = mk_rsrc(P);
;     const int rb2 = b * SEQ * INP * 2;
;     const rsrc_t ry = mk_rsrc(Y); const int yb2 = b * SEQ * D * 2, voY = (tg * D + 512 + ch) * 2;
;     const int voX = (tg * INP + ch) * 2;
;     ...
;     LRU_LOAD(0);
.LBB0_951:
	s_or_b64 exec, exec, s[4:5]
	s_mov_b64 s[4:5], s[0:1]
	s_load_dwordx2 s[4:5], s[4:5], 0x68
	s_mov_b64 s[6:7], 0x1000
	v_add_u32_e32 v135, s67, v135
	v_ashrrev_i32_e32 v179, 6, v135
	v_max_i32_e32 v164, 1, v179
	s_waitcnt lgkmcnt(0)
	v_lshl_add_u64 v[158:159], s[4:5], 0, v[36:37]
	v_lshl_add_u64 v[160:161], v[158:159], 0, s[6:7]
	v_add_co_u32_e32 v158, vcc, s63, v158
	s_mov_b64 s[4:5], s[0:1]
	s_nop 0
	v_addc_co_u32_e32 v159, vcc, 0, v159, vcc
	flat_load_dword v157, v[160:161] offset:1024
	s_nop 0
	flat_load_dword v158, v[158:159]
	s_nop 0
	flat_load_dword v159, v[160:161] offset:2048
	s_nop 0
	flat_load_dword v160, v[160:161] offset:3072
	s_load_dwordx2 s[4:5], s[4:5], 0x70
	v_mul_lo_u32 v161, v179, s78
	v_mul_lo_u32 v164, v164, s78
	v_or_b32_e32 v161, v161, v174
	v_or_b32_e32 v164, v164, v174
	s_waitcnt lgkmcnt(0)
	v_lshl_add_u64 v[162:163], s[4:5], 0, v[36:37]
	flat_load_dword v36, v[162:163] offset:1024
	v_max_i32_e32 v162, 3, v179
	v_max_i32_e32 v163, 2, v179
	v_mul_lo_u32 v162, v162, s78
	v_mul_lo_u32 v163, v163, s78
	v_or_b32_e32 v162, v162, v174
	v_or_b32_e32 v163, v163, v174
	v_lshlrev_b32_e32 v161, 1, v161
	s_or_b32 s4, s12, 0x1008
	s_or_b32 s5, s12, 0x1208
	v_lshl_add_u32 v162, v162, 1, v147
	v_lshl_add_u32 v163, v163, 1, v148
	v_lshl_add_u32 v164, v164, 1, v149
	buffer_load_ushort v175, v162, s[16:19], s5 offen
	buffer_load_ushort v176, v163, s[16:19], s5 offen
	buffer_load_ushort v177, v164, s[16:19], s5 offen
	s_or_b32 s6, s12, 0xf008
	s_or_b32 s7, s12, 0x9e08
	s_or_b32 s8, s12, 0xba08
	s_or_b32 s9, s12, 0xd608
	s_or_b32 s10, s12, 0xf208
	s_or_b32 s11, s12, 0x1d008
	buffer_load_ushort v207, v161, s[16:19], s4 offen
	buffer_load_ushort v162, v161, s[16:19], s5 offen
	buffer_load_ushort v202, v161, s[16:19], s6 offen
	buffer_load_ushort v163, v161, s[16:19], s7 offen
	buffer_load_ushort v164, v161, s[16:19], s8 offen
	buffer_load_ushort v165, v161, s[16:19], s9 offen
	buffer_load_ushort v166, v161, s[16:19], s10 offen
	buffer_load_ushort v197, v161, s[16:19], s11 offen
	s_or_b32 s4, s12, 0x17e08
	s_or_b32 s5, s12, 0x19a08
	s_or_b32 s6, s12, 0x1b608
	s_or_b32 s7, s12, 0x1d208
	s_or_b32 s8, s12, 0x2b008
	s_or_b32 s9, s12, 0x25e08
	s_or_b32 s10, s12, 0x27a08
	s_or_b32 s11, s12, 0x29608
	buffer_load_ushort v167, v161, s[16:19], s4 offen
	buffer_load_ushort v168, v161, s[16:19], s5 offen
	buffer_load_ushort v169, v161, s[16:19], s6 offen
	buffer_load_ushort v170, v161, s[16:19], s7 offen
	buffer_load_ushort v196, v161, s[16:19], s8 offen
	buffer_load_ushort v171, v161, s[16:19], s9 offen
	buffer_load_ushort v172, v161, s[16:19], s10 offen
	buffer_load_ushort v173, v161, s[16:19], s11 offen
	s_or_b32 s4, s12, 0x2b208
	s_or_b32 s5, s12, 0x39008
	s_or_b32 s6, s12, 0x33e08
	s_or_b32 s7, s12, 0x35a08
	s_or_b32 s8, s12, 0x37608
	s_or_b32 s9, s12, 0x39208
	s_or_b32 s10, s12, 0x47008
	s_or_b32 s11, s12, 0x41e08
	buffer_load_ushort v183, v161, s[16:19], s4 offen
	buffer_load_ushort v195, v161, s[16:19], s5 offen
	buffer_load_ushort v185, v161, s[16:19], s6 offen
	buffer_load_ushort v187, v161, s[16:19], s7 offen
	buffer_load_ushort v191, v161, s[16:19], s8 offen
	buffer_load_ushort v192, v161, s[16:19], s9 offen
	buffer_load_ushort v190, v161, s[16:19], s10 offen
	buffer_load_ushort v194, v161, s[16:19], s11 offen
	s_or_b32 s4, s12, 0x43a08
	s_or_b32 s5, s12, 0x45608
	s_or_b32 s6, s12, 0x47208
	s_or_b32 s7, s12, 0x55008
	s_or_b32 s8, s12, 0x4fe08
	s_or_b32 s9, s12, 0x51a08
	s_or_b32 s10, s12, 0x53608
	s_or_b32 s11, s12, 0x55208
	buffer_load_ushort v198, v161, s[16:19], s4 offen
	buffer_load_ushort v199, v161, s[16:19], s5 offen
	buffer_load_ushort v201, v161, s[16:19], s6 offen
	buffer_load_ushort v189, v161, s[16:19], s7 offen
	buffer_load_ushort v204, v161, s[16:19], s8 offen
	buffer_load_ushort v205, v161, s[16:19], s9 offen
	buffer_load_ushort v206, v161, s[16:19], s10 offen
	buffer_load_ushort v209, v161, s[16:19], s11 offen
	s_or_b32 s4, s12, 0x63008
	buffer_load_ushort v186, v161, s[16:19], s4 offen
	s_or_b32 s4, s12, 0x5de08
	s_or_b32 s5, s12, 0x5fa08
	s_or_b32 s6, s12, 0x61608
	s_or_b32 s7, s12, 0x63208
	buffer_load_ushort v211, v161, s[16:19], s4 offen
	buffer_load_ushort v212, v161, s[16:19], s5 offen
	buffer_load_ushort v213, v161, s[16:19], s6 offen
	buffer_load_ushort v215, v161, s[16:19], s7 offen
	v_cmp_lt_i32_e32 vcc, 2, v179
	v_lshlrev_b32_e32 v180, 1, v174
	v_lshlrev_b32_e32 v181, 11, v179
	s_movk_i32 s4, 0x400
	s_mov_b32 s9, 0
	s_or_b32 s8, s12, 0x70000
	s_waitcnt vmcnt(0)
; __device__ __forceinline__ float softplusf_(float x) { return x > 20.f ? x : log1pf(expf(x)); }
; __device__ __forceinline__ const float* argf(int i) { return (const float*)kargs()[i]; }
; __device__ __forceinline__ void lru_job(const bf16_t* P, bf16_t* Y, int l, int b, int kb, LAS float* lds, int wave_s) {
;     ...
;     f32x2_t wax[64];
;     { const float* wap = argf(15) + l * 16384; const float* wxp = argf(17) + l * 16384;
; #pragma unroll
;       for (int i = 0; i < 64; ++i) { wax[i].x = wap[(kb * 64 + i) * 64 + j]; wax[i].y = wxp[(kb * 64 + i) * 64 + j]; } }
;     const float ba = argf(16)[l * 256 + ch], bx = argf(18)[l * 256 + ch], spl = softplusf_(-argf(19)[l * 256 + ch]);
;     ...
;     LRU_LOAD(0);
	v_cndmask_b32_e32 v174, 0, v175, vcc
	v_cmp_lt_i32_e32 vcc, 1, v179
	v_or3_b32 v175, v181, v180, s4
	v_mov_b32_e32 v184, v207
	v_cndmask_b32_e32 v178, 0, v176, vcc
	v_cmp_lt_i32_e32 vcc, 0, v179
	v_add_u32_e32 v176, 0, v134
	v_or_b32_e32 v134, v181, v134
	v_cndmask_b32_e32 v182, 0, v177, vcc
	v_and_b32_e32 v177, 0x3fffffc0, v135
	v_lshl_add_u32 v177, v177, 2, v176
	v_cmp_gt_i32_e32 vcc, 64, v135
	v_lshl_add_u32 v179, v179, 8, v176
	v_add_u32_e32 v180, 0, v134
	v_add_u32_e32 v181, 0, v181
	v_mov_b32_e32 v135, 0
	v_mov_b32_e32 v200, v196
	v_mov_b32_e32 v193, v197
	v_mov_b32_e32 v188, v202
	v_mov_b32_e32 v203, v195
	v_mov_b32_e32 v208, v190
	v_mov_b32_e32 v210, v189
	v_mov_b32_e32 v214, v186
	v_mbcnt_lo_u32_b32 v101, -1, 0
	v_mbcnt_hi_u32_b32 v101, -1, v101
	v_and_b32_e32 v102, 15, v101
	v_lshrrev_b32_e32 v103, 4, v101
	s_lshr_b32 s4, s67, 6
	s_and_b32 s5, s4, 3
	s_lshr_b32 s4, s4, 2
	s_lshl_b32 s6, s4, 5
	s_lshl_b32 s7, s5, 4
	v_add_u32_e32 v104, s6, v102
	v_lshlrev_b32_e32 v105, 2, v104
	v_add_u32_e32 v111, 64, v105
	ds_bpermute_b32 v96, v105, v132
	ds_bpermute_b32 v97, v105, v133
	ds_bpermute_b32 v98, v105, v39
	ds_bpermute_b32 v107, v111, v132
	ds_bpermute_b32 v108, v111, v133
	ds_bpermute_b32 v109, v111, v39
	v_add_u32_e32 v99, s7, v102
	v_lshlrev_b32_e32 v99, 8, v99
	v_lshl_add_u32 v99, v103, 6, v99
	v_lshl_add_u32 v100, v103, 2, s7
	v_lshlrev_b32_e32 v100, 8, v100
	v_add_u32_e32 v100, v100, v105
	v_add_u32_e32 v110, 64, v100
	v_lshlrev_b32_e32 v106, 12, v103
	v_lshl_add_u32 v106, v102, 2, v106
	s_load_dwordx2 s[10:11], s[0:1], 0x78
	s_lshl_b32 s4, s70, 14
	s_lshl_b32 s6, s6, 2
	s_add_u32 s4, s4, s6
	s_add_u32 s4, s4, 0x10000
	s_waitcnt lgkmcnt(0)
	s_add_u32 s10, s10, s4
	s_addc_u32 s11, s11, 0
	s_nop 4
	global_load_dword v0, v106, s[10:11] offset:0
	global_load_dword v1, v106, s[10:11] offset:256
	global_load_dword v2, v106, s[10:11] offset:512
	global_load_dword v3, v106, s[10:11] offset:768
	global_load_dword v4, v106, s[10:11] offset:1024
	global_load_dword v5, v106, s[10:11] offset:1280
	global_load_dword v6, v106, s[10:11] offset:1536
	global_load_dword v7, v106, s[10:11] offset:1792
	global_load_dword v8, v106, s[10:11] offset:2048
	global_load_dword v9, v106, s[10:11] offset:2304
	global_load_dword v10, v106, s[10:11] offset:2560
	global_load_dword v11, v106, s[10:11] offset:2816
	global_load_dword v12, v106, s[10:11] offset:3072
	global_load_dword v13, v106, s[10:11] offset:3328
	global_load_dword v14, v106, s[10:11] offset:3584
	global_load_dword v15, v106, s[10:11] offset:3840
	global_load_dword v56, v106, s[10:11] offset:64
	global_load_dword v57, v106, s[10:11] offset:320
	global_load_dword v58, v106, s[10:11] offset:576
	global_load_dword v59, v106, s[10:11] offset:832
	global_load_dword v60, v106, s[10:11] offset:1088
	global_load_dword v61, v106, s[10:11] offset:1344
	global_load_dword v62, v106, s[10:11] offset:1600
	global_load_dword v63, v106, s[10:11] offset:1856
	global_load_dword v64, v106, s[10:11] offset:2112
	global_load_dword v65, v106, s[10:11] offset:2368
	global_load_dword v66, v106, s[10:11] offset:2624
	global_load_dword v67, v106, s[10:11] offset:2880
	global_load_dword v68, v106, s[10:11] offset:3136
	global_load_dword v69, v106, s[10:11] offset:3392
	global_load_dword v70, v106, s[10:11] offset:3648
	global_load_dword v71, v106, s[10:11] offset:3904
	s_load_dwordx2 s[10:11], s[0:1], 0x88
	s_waitcnt lgkmcnt(0)
	s_add_u32 s10, s10, s4
	s_addc_u32 s11, s11, 0
	s_nop 4
	global_load_dword v16, v106, s[10:11] offset:0
	global_load_dword v17, v106, s[10:11] offset:256
	global_load_dword v18, v106, s[10:11] offset:512
	global_load_dword v19, v106, s[10:11] offset:768
	global_load_dword v20, v106, s[10:11] offset:1024
	global_load_dword v21, v106, s[10:11] offset:1280
	global_load_dword v22, v106, s[10:11] offset:1536
	global_load_dword v23, v106, s[10:11] offset:1792
	global_load_dword v24, v106, s[10:11] offset:2048
	global_load_dword v25, v106, s[10:11] offset:2304
	global_load_dword v26, v106, s[10:11] offset:2560
	global_load_dword v27, v106, s[10:11] offset:2816
	global_load_dword v28, v106, s[10:11] offset:3072
	global_load_dword v29, v106, s[10:11] offset:3328
	global_load_dword v30, v106, s[10:11] offset:3584
	global_load_dword v31, v106, s[10:11] offset:3840
	global_load_dword v112, v106, s[10:11] offset:64
	global_load_dword v113, v106, s[10:11] offset:320
	global_load_dword v114, v106, s[10:11] offset:576
	global_load_dword v115, v106, s[10:11] offset:832
	global_load_dword v116, v106, s[10:11] offset:1088
	global_load_dword v117, v106, s[10:11] offset:1344
	global_load_dword v118, v106, s[10:11] offset:1600
	global_load_dword v119, v106, s[10:11] offset:1856
	global_load_dword v120, v106, s[10:11] offset:2112
	global_load_dword v121, v106, s[10:11] offset:2368
	global_load_dword v122, v106, s[10:11] offset:2624
	global_load_dword v123, v106, s[10:11] offset:2880
	global_load_dword v124, v106, s[10:11] offset:3136
	global_load_dword v125, v106, s[10:11] offset:3392
	global_load_dword v126, v106, s[10:11] offset:3648
	global_load_dword v127, v106, s[10:11] offset:3904
	s_waitcnt vmcnt(0)
	s_branch .LBB0_953

; #define LAS __attribute__((address_space(3)))
; __device__ __forceinline__ void lru_job(const bf16_t* P, bf16_t* Y, int l, int b, int kb, LAS float* lds, int wave_s) {
;     ...
;         for (int tt = 0; tt < 8; ++tt) { const int t = tg * 8 + tt; f32x2_t dd = {ba, bx};
; #pragma unroll
;             for (int i4 = 0; i4 < 16; ++i4) { const f32x4 xv = *(const LAS f32x4*)(XC + t * 64 + 4 * i4);
; #pragma unroll
;                 for (int q = 0; q < 4; ++q) { const f32x2_t xb = {xv[q], xv[q]}; dd = __builtin_elementwise_fma(xb, wax[4 * i4 + q], dd); } }
.LBB0_955:
	ds_read_b128 v[40:43], v99
	ds_read_b128 v[44:47], v99 offset:16
	ds_read_b128 v[48:51], v99 offset:32
	ds_read_b128 v[52:55], v99 offset:48
	ds_read_b32 v88, v100
	ds_read_b32 v89, v100 offset:256
	ds_read_b32 v90, v100 offset:512
	ds_read_b32 v91, v100 offset:768
	ds_read_b32 v92, v110
	ds_read_b32 v93, v110 offset:256
	ds_read_b32 v94, v110 offset:512
	ds_read_b32 v95, v110 offset:768
	v_mov_b32_e32 v72, v96
	v_mov_b32_e32 v73, v96
	v_mov_b32_e32 v74, v96
	v_mov_b32_e32 v75, v96
	v_mov_b32_e32 v76, v97
	v_mov_b32_e32 v77, v97
	v_mov_b32_e32 v78, v97
	v_mov_b32_e32 v79, v97
	v_mov_b32_e32 v80, v107
	v_mov_b32_e32 v81, v107
	v_mov_b32_e32 v82, v107
	v_mov_b32_e32 v83, v107
	v_mov_b32_e32 v84, v108
	v_mov_b32_e32 v85, v108
	v_mov_b32_e32 v86, v108
	v_mov_b32_e32 v87, v108
	s_waitcnt lgkmcnt(11)
	s_nop 1
	v_mfma_f32_16x16x4_f32 v[72:75], v40, v0, v[72:75]
	v_mfma_f32_16x16x4_f32 v[76:79], v40, v16, v[76:79]
	v_mfma_f32_16x16x4_f32 v[80:83], v40, v56, v[80:83]
	v_mfma_f32_16x16x4_f32 v[84:87], v40, v112, v[84:87]
	v_mfma_f32_16x16x4_f32 v[72:75], v41, v1, v[72:75]
	v_mfma_f32_16x16x4_f32 v[76:79], v41, v17, v[76:79]
	v_mfma_f32_16x16x4_f32 v[80:83], v41, v57, v[80:83]
	v_mfma_f32_16x16x4_f32 v[84:87], v41, v113, v[84:87]
	v_mfma_f32_16x16x4_f32 v[72:75], v42, v2, v[72:75]
	v_mfma_f32_16x16x4_f32 v[76:79], v42, v18, v[76:79]
	v_mfma_f32_16x16x4_f32 v[80:83], v42, v58, v[80:83]
	v_mfma_f32_16x16x4_f32 v[84:87], v42, v114, v[84:87]
	v_mfma_f32_16x16x4_f32 v[72:75], v43, v3, v[72:75]
	v_mfma_f32_16x16x4_f32 v[76:79], v43, v19, v[76:79]
	v_mfma_f32_16x16x4_f32 v[80:83], v43, v59, v[80:83]
	v_mfma_f32_16x16x4_f32 v[84:87], v43, v115, v[84:87]
	s_waitcnt lgkmcnt(10)
	v_mfma_f32_16x16x4_f32 v[72:75], v44, v4, v[72:75]
	v_mfma_f32_16x16x4_f32 v[76:79], v44, v20, v[76:79]
	v_mfma_f32_16x16x4_f32 v[80:83], v44, v60, v[80:83]
	v_mfma_f32_16x16x4_f32 v[84:87], v44, v116, v[84:87]
	v_mfma_f32_16x16x4_f32 v[72:75], v45, v5, v[72:75]
	v_mfma_f32_16x16x4_f32 v[76:79], v45, v21, v[76:79]
	v_mfma_f32_16x16x4_f32 v[80:83], v45, v61, v[80:83]
	v_mfma_f32_16x16x4_f32 v[84:87], v45, v117, v[84:87]
	v_mfma_f32_16x16x4_f32 v[72:75], v46, v6, v[72:75]
	v_mfma_f32_16x16x4_f32 v[76:79], v46, v22, v[76:79]
	v_mfma_f32_16x16x4_f32 v[80:83], v46, v62, v[80:83]
	v_mfma_f32_16x16x4_f32 v[84:87], v46, v118, v[84:87]
	v_mfma_f32_16x16x4_f32 v[72:75], v47, v7, v[72:75]
	v_mfma_f32_16x16x4_f32 v[76:79], v47, v23, v[76:79]
	v_mfma_f32_16x16x4_f32 v[80:83], v47, v63, v[80:83]
	v_mfma_f32_16x16x4_f32 v[84:87], v47, v119, v[84:87]
	s_waitcnt lgkmcnt(9)
	v_mfma_f32_16x16x4_f32 v[72:75], v48, v8, v[72:75]
	v_mfma_f32_16x16x4_f32 v[76:79], v48, v24, v[76:79]
	v_mfma_f32_16x16x4_f32 v[80:83], v48, v64, v[80:83]
	v_mfma_f32_16x16x4_f32 v[84:87], v48, v120, v[84:87]
	v_mfma_f32_16x16x4_f32 v[72:75], v49, v9, v[72:75]
	v_mfma_f32_16x16x4_f32 v[76:79], v49, v25, v[76:79]
	v_mfma_f32_16x16x4_f32 v[80:83], v49, v65, v[80:83]
	v_mfma_f32_16x16x4_f32 v[84:87], v49, v121, v[84:87]
	v_mfma_f32_16x16x4_f32 v[72:75], v50, v10, v[72:75]
	v_mfma_f32_16x16x4_f32 v[76:79], v50, v26, v[76:79]
	v_mfma_f32_16x16x4_f32 v[80:83], v50, v66, v[80:83]
	v_mfma_f32_16x16x4_f32 v[84:87], v50, v122, v[84:87]
	v_mfma_f32_16x16x4_f32 v[72:75], v51, v11, v[72:75]
	v_mfma_f32_16x16x4_f32 v[76:79], v51, v27, v[76:79]
	v_mfma_f32_16x16x4_f32 v[80:83], v51, v67, v[80:83]
	v_mfma_f32_16x16x4_f32 v[84:87], v51, v123, v[84:87]
	s_waitcnt lgkmcnt(8)
	v_mfma_f32_16x16x4_f32 v[72:75], v52, v12, v[72:75]
	v_mfma_f32_16x16x4_f32 v[76:79], v52, v28, v[76:79]
	v_mfma_f32_16x16x4_f32 v[80:83], v52, v68, v[80:83]
	v_mfma_f32_16x16x4_f32 v[84:87], v52, v124, v[84:87]
	v_mfma_f32_16x16x4_f32 v[72:75], v53, v13, v[72:75]
	v_mfma_f32_16x16x4_f32 v[76:79], v53, v29, v[76:79]
	v_mfma_f32_16x16x4_f32 v[80:83], v53, v69, v[80:83]
	v_mfma_f32_16x16x4_f32 v[84:87], v53, v125, v[84:87]
	v_mfma_f32_16x16x4_f32 v[72:75], v54, v14, v[72:75]
	v_mfma_f32_16x16x4_f32 v[76:79], v54, v30, v[76:79]
	v_mfma_f32_16x16x4_f32 v[80:83], v54, v70, v[80:83]
	v_mfma_f32_16x16x4_f32 v[84:87], v54, v126, v[84:87]
	v_mfma_f32_16x16x4_f32 v[72:75], v55, v15, v[72:75]
	v_mfma_f32_16x16x4_f32 v[76:79], v55, v31, v[76:79]
	v_mfma_f32_16x16x4_f32 v[80:83], v55, v71, v[80:83]
	v_mfma_f32_16x16x4_f32 v[84:87], v55, v127, v[84:87]
	s_waitcnt lgkmcnt(0)
; __device__ __forceinline__ float sigmoidf_(float x) { return __builtin_amdgcn_rcpf(1.f + __expf(-x)); }
; __device__ __forceinline__ void lru_job(const bf16_t* P, bf16_t* Y, int l, int b, int kb, LAS float* lds, int wave_s) {
;     ...
;             const float rg = sigmoidf_(dd.x), ig = sigmoidf_(dd.y);
;             const float la = -8.f * rg * spl;
;             const float av = __expf(la);
;             Aa[t * 64 + j] = av;
;             Uu[t * 64 + j] = sqrtf(fmaxf(1.f - av * av, 0.f)) * (ig * XC[t * 64 + j]); }
	s_nop 7
	s_nop 3
	v_mul_f32_e32 v101, 0xbfb8aa3b, v72
	v_mul_f32_e32 v104, 0xbfb8aa3b, v73
	v_exp_f32_e32 v101, v101
	v_exp_f32_e32 v104, v104
	v_mul_f32_e32 v102, 0xbfb8aa3b, v76
	v_mul_f32_e32 v105, 0xbfb8aa3b, v77
	v_exp_f32_e32 v102, v102
	v_exp_f32_e32 v105, v105
	v_add_f32_e32 v101, 1.0, v101
	v_add_f32_e32 v104, 1.0, v104
	v_rcp_f32_e32 v101, v101
	v_rcp_f32_e32 v104, v104
	v_add_f32_e32 v102, 1.0, v102
	v_add_f32_e32 v105, 1.0, v105
	v_rcp_f32_e32 v102, v102
	v_rcp_f32_e32 v105, v105
	v_mul_f32_e32 v101, 0xc1000000, v101
	v_mul_f32_e32 v104, 0xc1000000, v104
	v_mul_f32_e32 v101, v98, v101
	v_mul_f32_e32 v104, v98, v104
	v_mul_f32_e32 v101, 0x3fb8aa3b, v101
	v_mul_f32_e32 v104, 0x3fb8aa3b, v104
	v_exp_f32_e32 v101, v101
	v_exp_f32_e32 v104, v104
	v_mul_f32_e32 v102, v88, v102
	v_mul_f32_e32 v105, v89, v105
	v_fma_f32 v103, -v101, v101, 1.0
	v_fma_f32 v106, -v104, v104, 1.0
	v_max_f32_e32 v103, 0, v103
	v_max_f32_e32 v106, 0, v106
	v_sqrt_f32_e32 v103, v103
	v_sqrt_f32_e32 v106, v106
	s_nop 0
	s_nop 0
	v_mul_f32_e32 v102, v102, v103
	v_mul_f32_e32 v105, v105, v106
	ds_write2st64_b32 v100, v101, v102 offset0:64 offset1:128
	ds_write2st64_b32 v100, v104, v105 offset0:65 offset1:129
	v_mul_f32_e32 v101, 0xbfb8aa3b, v74
	v_mul_f32_e32 v104, 0xbfb8aa3b, v75
	v_exp_f32_e32 v101, v101
	v_exp_f32_e32 v104, v104
	v_mul_f32_e32 v102, 0xbfb8aa3b, v78
	v_mul_f32_e32 v105, 0xbfb8aa3b, v79
	v_exp_f32_e32 v102, v102
	v_exp_f32_e32 v105, v105
	v_add_f32_e32 v101, 1.0, v101
	v_add_f32_e32 v104, 1.0, v104
	v_rcp_f32_e32 v101, v101
	v_rcp_f32_e32 v104, v104
	v_add_f32_e32 v102, 1.0, v102
	v_add_f32_e32 v105, 1.0, v105
	v_rcp_f32_e32 v102, v102
	v_rcp_f32_e32 v105, v105
	v_mul_f32_e32 v101, 0xc1000000, v101
	v_mul_f32_e32 v104, 0xc1000000, v104
	v_mul_f32_e32 v101, v98, v101
	v_mul_f32_e32 v104, v98, v104
	v_mul_f32_e32 v101, 0x3fb8aa3b, v101
	v_mul_f32_e32 v104, 0x3fb8aa3b, v104
	v_exp_f32_e32 v101, v101
	v_exp_f32_e32 v104, v104
	v_mul_f32_e32 v102, v90, v102
	v_mul_f32_e32 v105, v91, v105
	v_fma_f32 v103, -v101, v101, 1.0
	v_fma_f32 v106, -v104, v104, 1.0
	v_max_f32_e32 v103, 0, v103
	v_max_f32_e32 v106, 0, v106
	v_sqrt_f32_e32 v103, v103
	v_sqrt_f32_e32 v106, v106
	s_nop 0
	s_nop 0
	v_mul_f32_e32 v102, v102, v103
	v_mul_f32_e32 v105, v105, v106
	ds_write2st64_b32 v100, v101, v102 offset0:66 offset1:130
	ds_write2st64_b32 v100, v104, v105 offset0:67 offset1:131
	v_mul_f32_e32 v101, 0xbfb8aa3b, v80
	v_mul_f32_e32 v104, 0xbfb8aa3b, v81
	v_exp_f32_e32 v101, v101
	v_exp_f32_e32 v104, v104
	v_mul_f32_e32 v102, 0xbfb8aa3b, v84
	v_mul_f32_e32 v105, 0xbfb8aa3b, v85
	v_exp_f32_e32 v102, v102
	v_exp_f32_e32 v105, v105
	v_add_f32_e32 v101, 1.0, v101
	v_add_f32_e32 v104, 1.0, v104
	v_rcp_f32_e32 v101, v101
	v_rcp_f32_e32 v104, v104
	v_add_f32_e32 v102, 1.0, v102
	v_add_f32_e32 v105, 1.0, v105
	v_rcp_f32_e32 v102, v102
	v_rcp_f32_e32 v105, v105
	v_mul_f32_e32 v101, 0xc1000000, v101
	v_mul_f32_e32 v104, 0xc1000000, v104
	v_mul_f32_e32 v101, v109, v101
	v_mul_f32_e32 v104, v109, v104
	v_mul_f32_e32 v101, 0x3fb8aa3b, v101
	v_mul_f32_e32 v104, 0x3fb8aa3b, v104
	v_exp_f32_e32 v101, v101
	v_exp_f32_e32 v104, v104
	v_mul_f32_e32 v102, v92, v102
	v_mul_f32_e32 v105, v93, v105
	v_fma_f32 v103, -v101, v101, 1.0
	v_fma_f32 v106, -v104, v104, 1.0
	v_max_f32_e32 v103, 0, v103
	v_max_f32_e32 v106, 0, v106
	v_sqrt_f32_e32 v103, v103
	v_sqrt_f32_e32 v106, v106
	s_nop 0
	s_nop 0
	v_mul_f32_e32 v102, v102, v103
	v_mul_f32_e32 v105, v105, v106
	ds_write2st64_b32 v110, v101, v102 offset0:64 offset1:128
	ds_write2st64_b32 v110, v104, v105 offset0:65 offset1:129
	v_mul_f32_e32 v101, 0xbfb8aa3b, v82
	v_mul_f32_e32 v104, 0xbfb8aa3b, v83
	v_exp_f32_e32 v101, v101
	v_exp_f32_e32 v104, v104
	v_mul_f32_e32 v102, 0xbfb8aa3b, v86
	v_mul_f32_e32 v105, 0xbfb8aa3b, v87
	v_exp_f32_e32 v102, v102
	v_exp_f32_e32 v105, v105
	v_add_f32_e32 v101, 1.0, v101
	v_add_f32_e32 v104, 1.0, v104
	v_rcp_f32_e32 v101, v101
	v_rcp_f32_e32 v104, v104
	v_add_f32_e32 v102, 1.0, v102
	v_add_f32_e32 v105, 1.0, v105
	v_rcp_f32_e32 v102, v102
	v_rcp_f32_e32 v105, v105
	v_mul_f32_e32 v101, 0xc1000000, v101
	v_mul_f32_e32 v104, 0xc1000000, v104
	v_mul_f32_e32 v101, v109, v101
	v_mul_f32_e32 v104, v109, v104
	v_mul_f32_e32 v101, 0x3fb8aa3b, v101
	v_mul_f32_e32 v104, 0x3fb8aa3b, v104
	v_exp_f32_e32 v101, v101
	v_exp_f32_e32 v104, v104
	v_mul_f32_e32 v102, v94, v102
	v_mul_f32_e32 v105, v95, v105
	v_fma_f32 v103, -v101, v101, 1.0
	v_fma_f32 v106, -v104, v104, 1.0
	v_max_f32_e32 v103, 0, v103
	v_max_f32_e32 v106, 0, v106
	v_sqrt_f32_e32 v103, v103
	v_sqrt_f32_e32 v106, v106
	s_nop 0
	s_nop 0
	v_mul_f32_e32 v102, v102, v103
	v_mul_f32_e32 v105, v105, v106
	ds_write2st64_b32 v110, v101, v102 offset0:66 offset1:130
	ds_write2st64_b32 v110, v104, v105 offset0:67 offset1:131
	s_waitcnt lgkmcnt(0)
	s_barrier
	s_and_saveexec_b64 s[4:5], vcc
	s_cbranch_execz .LBB0_952
; __device__ __forceinline__ void lru_job(const bf16_t* P, bf16_t* Y, int l, int b, int kb, LAS float* lds, int wave_s) {
;     ...
;         if (tid < 64) {
;             for (int tb = 0; tb < TC; tb += 8) { float av[8], uv[8];
; #pragma unroll
;                 for (int k = 0; k < 8; ++k) { av[k] = Aa[(tb + k) * 64 + j]; uv[k] = Uu[(tb + k) * 64 + j]; }
; #pragma unroll
;                 for (int k = 0; k < 8; ++k) { hs = av[k] * hs + uv[k]; Hh[(tb + k) * 64 + j] = hs; } }
;         }
	ds_read2st64_b32 v[216:217], v176 offset0:64 offset1:65
	ds_read2st64_b32 v[218:219], v176 offset0:66 offset1:67
	ds_read2st64_b32 v[220:221], v176 offset0:68 offset1:69
	ds_read2st64_b32 v[222:223], v176 offset0:70 offset1:71
	ds_read2st64_b32 v[224:225], v176 offset0:128 offset1:129
	ds_read2st64_b32 v[226:227], v176 offset0:130 offset1:131
	ds_read2st64_b32 v[228:229], v176 offset0:132 offset1:133
	ds_read2st64_b32 v[230:231], v176 offset0:134 offset1:135
	ds_read2st64_b32 v[234:235], v176 offset0:72 offset1:73
	ds_read2st64_b32 v[236:237], v176 offset0:74 offset1:75
	ds_read2st64_b32 v[238:239], v176 offset0:76 offset1:77
	ds_read2st64_b32 v[240:241], v176 offset0:78 offset1:79
	ds_read2st64_b32 v[242:243], v176 offset0:136 offset1:137
	ds_read2st64_b32 v[244:245], v176 offset0:138 offset1:139
	ds_read2st64_b32 v[246:247], v176 offset0:140 offset1:141
	ds_read2st64_b32 v[248:249], v176 offset0:142 offset1:143
	s_waitcnt lgkmcnt(8)
	v_fmac_f32_e32 v224, v135, v216
	v_fmac_f32_e32 v225, v224, v217
	v_fmac_f32_e32 v226, v225, v218
	v_fmac_f32_e32 v227, v226, v219
	v_fmac_f32_e32 v228, v227, v220
	v_fmac_f32_e32 v229, v228, v221
	v_fmac_f32_e32 v230, v229, v222
	v_fmac_f32_e32 v231, v230, v223
	ds_write2st64_b32 v176, v224, v225 offset0:192 offset1:193
	ds_write2st64_b32 v176, v226, v227 offset0:194 offset1:195
	ds_write2st64_b32 v176, v228, v229 offset0:196 offset1:197
	ds_write2st64_b32 v176, v230, v231 offset0:198 offset1:199
	ds_read2st64_b32 v[216:217], v176 offset0:80 offset1:81
	ds_read2st64_b32 v[218:219], v176 offset0:82 offset1:83
	ds_read2st64_b32 v[220:221], v176 offset0:84 offset1:85
	ds_read2st64_b32 v[222:223], v176 offset0:86 offset1:87
	ds_read2st64_b32 v[224:225], v176 offset0:144 offset1:145
	ds_read2st64_b32 v[226:227], v176 offset0:146 offset1:147
	ds_read2st64_b32 v[228:229], v176 offset0:148 offset1:149
	ds_read2st64_b32 v[230:231], v176 offset0:150 offset1:151
	s_waitcnt lgkmcnt(12)
	v_fmac_f32_e32 v242, v231, v234
	v_fmac_f32_e32 v243, v242, v235
	v_fmac_f32_e32 v244, v243, v236
	v_fmac_f32_e32 v245, v244, v237
	v_fmac_f32_e32 v246, v245, v238
	v_fmac_f32_e32 v247, v246, v239
	v_fmac_f32_e32 v248, v247, v240
	v_fmac_f32_e32 v249, v248, v241
	ds_write2st64_b32 v176, v242, v243 offset0:200 offset1:201
	ds_write2st64_b32 v176, v244, v245 offset0:202 offset1:203
	ds_write2st64_b32 v176, v246, v247 offset0:204 offset1:205
	ds_write2st64_b32 v176, v248, v249 offset0:206 offset1:207
	ds_read2st64_b32 v[234:235], v176 offset0:88 offset1:89
	ds_read2st64_b32 v[236:237], v176 offset0:90 offset1:91
	ds_read2st64_b32 v[238:239], v176 offset0:92 offset1:93
	ds_read2st64_b32 v[240:241], v176 offset0:94 offset1:95
	ds_read2st64_b32 v[242:243], v176 offset0:152 offset1:153
	ds_read2st64_b32 v[244:245], v176 offset0:154 offset1:155
	ds_read2st64_b32 v[246:247], v176 offset0:156 offset1:157
	ds_read2st64_b32 v[248:249], v176 offset0:158 offset1:159
	s_waitcnt lgkmcnt(12)
	v_fmac_f32_e32 v224, v249, v216
	v_fmac_f32_e32 v225, v224, v217
	v_fmac_f32_e32 v226, v225, v218
	v_fmac_f32_e32 v227, v226, v219
	v_fmac_f32_e32 v228, v227, v220
	v_fmac_f32_e32 v229, v228, v221
	v_fmac_f32_e32 v230, v229, v222
	v_fmac_f32_e32 v231, v230, v223
	ds_write2st64_b32 v176, v224, v225 offset0:208 offset1:209
	ds_write2st64_b32 v176, v226, v227 offset0:210 offset1:211
	ds_write2st64_b32 v176, v228, v229 offset0:212 offset1:213
	ds_write2st64_b32 v176, v230, v231 offset0:214 offset1:215
	ds_read2st64_b32 v[216:217], v176 offset0:96 offset1:97
	ds_read2st64_b32 v[218:219], v176 offset0:98 offset1:99
	ds_read2st64_b32 v[220:221], v176 offset0:100 offset1:101
	ds_read2st64_b32 v[222:223], v176 offset0:102 offset1:103
	ds_read2st64_b32 v[224:225], v176 offset0:160 offset1:161
	ds_read2st64_b32 v[226:227], v176 offset0:162 offset1:163
	ds_read2st64_b32 v[228:229], v176 offset0:164 offset1:165
	ds_read2st64_b32 v[230:231], v176 offset0:166 offset1:167
	s_waitcnt lgkmcnt(12)
; __device__ __forceinline__ void lru_job(const bf16_t* P, bf16_t* Y, int l, int b, int kb, LAS float* lds, int wave_s) {
;     ...
;         if (tid < 64) {
;             for (int tb = 0; tb < TC; tb += 8) { float av[8], uv[8];
; #pragma unroll
;                 for (int k = 0; k < 8; ++k) { av[k] = Aa[(tb + k) * 64 + j]; uv[k] = Uu[(tb + k) * 64 + j]; }
; #pragma unroll
;                 for (int k = 0; k < 8; ++k) { hs = av[k] * hs + uv[k]; Hh[(tb + k) * 64 + j] = hs; } }
;         }
	v_fmac_f32_e32 v242, v231, v234
	v_fmac_f32_e32 v243, v242, v235
	v_fmac_f32_e32 v244, v243, v236
	v_fmac_f32_e32 v245, v244, v237
	v_fmac_f32_e32 v246, v245, v238
	v_fmac_f32_e32 v247, v246, v239
	v_fmac_f32_e32 v248, v247, v240
	v_fmac_f32_e32 v249, v248, v241
	ds_write2st64_b32 v176, v242, v243 offset0:216 offset1:217
	ds_write2st64_b32 v176, v244, v245 offset0:218 offset1:219
	ds_write2st64_b32 v176, v246, v247 offset0:220 offset1:221
	ds_write2st64_b32 v176, v248, v249 offset0:222 offset1:223
	ds_read2st64_b32 v[234:235], v176 offset0:104 offset1:105
	ds_read2st64_b32 v[236:237], v176 offset0:106 offset1:107
	ds_read2st64_b32 v[238:239], v176 offset0:108 offset1:109
	ds_read2st64_b32 v[240:241], v176 offset0:110 offset1:111
	ds_read2st64_b32 v[242:243], v176 offset0:168 offset1:169
	ds_read2st64_b32 v[244:245], v176 offset0:170 offset1:171
	ds_read2st64_b32 v[246:247], v176 offset0:172 offset1:173
	ds_read2st64_b32 v[248:249], v176 offset0:174 offset1:175
	s_waitcnt lgkmcnt(12)
	v_fmac_f32_e32 v224, v249, v216
	v_fmac_f32_e32 v225, v224, v217
	v_fmac_f32_e32 v226, v225, v218
	v_fmac_f32_e32 v227, v226, v219
	v_fmac_f32_e32 v228, v227, v220
	v_fmac_f32_e32 v229, v228, v221
	v_fmac_f32_e32 v230, v229, v222
	v_fmac_f32_e32 v231, v230, v223
	ds_write2st64_b32 v176, v224, v225 offset0:224 offset1:225
	ds_write2st64_b32 v176, v226, v227 offset0:226 offset1:227
	ds_write2st64_b32 v176, v228, v229 offset0:228 offset1:229
	ds_write2st64_b32 v176, v230, v231 offset0:230 offset1:231
	ds_read2st64_b32 v[216:217], v176 offset0:112 offset1:113
	ds_read2st64_b32 v[218:219], v176 offset0:114 offset1:115
	ds_read2st64_b32 v[220:221], v176 offset0:116 offset1:117
	ds_read2st64_b32 v[222:223], v176 offset0:118 offset1:119
	ds_read2st64_b32 v[224:225], v176 offset0:176 offset1:177
	ds_read2st64_b32 v[226:227], v176 offset0:178 offset1:179
	ds_read2st64_b32 v[228:229], v176 offset0:180 offset1:181
	ds_read2st64_b32 v[230:231], v176 offset0:182 offset1:183
	s_waitcnt lgkmcnt(12)
	v_fmac_f32_e32 v242, v231, v234
	v_fmac_f32_e32 v243, v242, v235
	v_fmac_f32_e32 v244, v243, v236
	v_fmac_f32_e32 v245, v244, v237
	v_fmac_f32_e32 v246, v245, v238
	v_fmac_f32_e32 v247, v246, v239
	v_fmac_f32_e32 v248, v247, v240
	v_fmac_f32_e32 v249, v248, v241
	ds_write2st64_b32 v176, v242, v243 offset0:232 offset1:233
	ds_write2st64_b32 v176, v244, v245 offset0:234 offset1:235
	ds_write2st64_b32 v176, v246, v247 offset0:236 offset1:237
	ds_write2st64_b32 v176, v248, v249 offset0:238 offset1:239
	ds_read2st64_b32 v[234:235], v176 offset0:120 offset1:121
	ds_read2st64_b32 v[236:237], v176 offset0:122 offset1:123
	ds_read2st64_b32 v[238:239], v176 offset0:124 offset1:125
	ds_read2st64_b32 v[240:241], v176 offset0:126 offset1:127
	ds_read2st64_b32 v[242:243], v176 offset0:184 offset1:185
	ds_read2st64_b32 v[244:245], v176 offset0:186 offset1:187
	ds_read2st64_b32 v[246:247], v176 offset0:188 offset1:189
	ds_read2st64_b32 v[248:249], v176 offset0:190 offset1:191
	s_waitcnt lgkmcnt(12)
	v_fmac_f32_e32 v224, v249, v216
	v_fmac_f32_e32 v225, v224, v217
	v_fmac_f32_e32 v226, v225, v218
	v_fmac_f32_e32 v227, v226, v219
	v_fmac_f32_e32 v228, v227, v220
	v_fmac_f32_e32 v229, v228, v221
	v_fmac_f32_e32 v230, v229, v222
	v_fmac_f32_e32 v231, v230, v223
	ds_write2st64_b32 v176, v224, v225 offset0:240 offset1:241
	ds_write2st64_b32 v176, v226, v227 offset0:242 offset1:243
	ds_write2st64_b32 v176, v228, v229 offset0:244 offset1:245
	ds_write2st64_b32 v176, v230, v231 offset0:246 offset1:247
	s_waitcnt lgkmcnt(4)
	v_fmac_f32_e32 v242, v231, v234
	v_fmac_f32_e32 v243, v242, v235
	v_fmac_f32_e32 v244, v243, v236
	v_fmac_f32_e32 v245, v244, v237
	v_fmac_f32_e32 v246, v245, v238
	v_fmac_f32_e32 v247, v246, v239
	v_fmac_f32_e32 v248, v247, v240
	v_fmac_f32_e32 v249, v248, v241
	ds_write2st64_b32 v176, v242, v243 offset0:248 offset1:249
	ds_write2st64_b32 v176, v244, v245 offset0:250 offset1:251
	ds_write2st64_b32 v176, v246, v247 offset0:252 offset1:253
	ds_write2st64_b32 v176, v248, v249 offset0:254 offset1:255
	v_mov_b32_e32 v135, v249
	s_branch .LBB0_952
